# adaLN GEMV k-block loop rewritten with all 32 row loads in flight; silu(c) fill loads batched
# speedup vs baseline: 1.0188x; 1.0121x over previous
.LBB0_779:
	s_and_saveexec_b64 s[0:1], s[4:5]
	s_cbranch_execz .LBB0_786
	v_lshlrev_b32_e32 v0, 2, v239
	global_load_dword v100, v0, s[46:47]
	global_load_dword v101, v0, s[46:47] offset:2048
	global_load_dword v102, v0, s[44:45]
	global_load_dword v103, v0, s[44:45] offset:2048
	v_add_u32_e32 v138, 0x1000, v0
	global_load_dword v104, v138, s[44:45]
	v_add_u32_e32 v139, 0x1800, v0
	global_load_dword v105, v139, s[44:45]
	v_add_u32_e32 v140, 0x2000, v0
	global_load_dword v106, v140, s[44:45]
	v_add_u32_e32 v141, 0x2800, v0
	global_load_dword v107, v141, s[44:45]
	v_add_u32_e32 v142, 0x3000, v0
	global_load_dword v108, v142, s[44:45]
	v_add_u32_e32 v143, 0x3800, v0
	global_load_dword v109, v143, s[44:45]
	v_add_u32_e32 v144, 0x4000, v0
	global_load_dword v110, v144, s[44:45]
	v_add_u32_e32 v145, 0x4800, v0
	global_load_dword v111, v145, s[44:45]
	v_add_u32_e32 v146, 0x5000, v0
	global_load_dword v112, v146, s[44:45]
	v_add_u32_e32 v147, 0x5800, v0
	global_load_dword v113, v147, s[44:45]
	v_add_u32_e32 v148, 0x6000, v0
	global_load_dword v114, v148, s[44:45]
	v_add_u32_e32 v149, 0x6800, v0
	global_load_dword v115, v149, s[44:45]
	v_add_u32_e32 v150, 0x7000, v0
	global_load_dword v116, v150, s[44:45]
	v_add_u32_e32 v151, 0x7800, v0
	global_load_dword v117, v151, s[44:45]
	s_waitcnt vmcnt(0)
	v_mul_f32_e32 v118, 0xbfb8aa3b, v100
	v_mul_f32_e32 v119, 0xbfb8aa3b, v101
	v_mul_f32_e32 v120, 0xbfb8aa3b, v102
	v_mul_f32_e32 v121, 0xbfb8aa3b, v103
	v_mul_f32_e32 v122, 0xbfb8aa3b, v104
	v_mul_f32_e32 v123, 0xbfb8aa3b, v105
	v_mul_f32_e32 v124, 0xbfb8aa3b, v106
	v_mul_f32_e32 v125, 0xbfb8aa3b, v107
	v_mul_f32_e32 v126, 0xbfb8aa3b, v108
	v_mul_f32_e32 v127, 0xbfb8aa3b, v109
	v_mul_f32_e32 v128, 0xbfb8aa3b, v110
	v_mul_f32_e32 v129, 0xbfb8aa3b, v111
	v_mul_f32_e32 v130, 0xbfb8aa3b, v112
	v_mul_f32_e32 v131, 0xbfb8aa3b, v113
	v_mul_f32_e32 v132, 0xbfb8aa3b, v114
	v_mul_f32_e32 v133, 0xbfb8aa3b, v115
	v_mul_f32_e32 v134, 0xbfb8aa3b, v116
	v_mul_f32_e32 v135, 0xbfb8aa3b, v117
	v_exp_f32_e32 v118, v118
	v_exp_f32_e32 v119, v119
	v_exp_f32_e32 v120, v120
	v_exp_f32_e32 v121, v121
	v_exp_f32_e32 v122, v122
	v_exp_f32_e32 v123, v123
	v_exp_f32_e32 v124, v124
	v_exp_f32_e32 v125, v125
	v_exp_f32_e32 v126, v126
	v_exp_f32_e32 v127, v127
	v_exp_f32_e32 v128, v128
	v_exp_f32_e32 v129, v129
	v_exp_f32_e32 v130, v130
	v_exp_f32_e32 v131, v131
	v_exp_f32_e32 v132, v132
	v_exp_f32_e32 v133, v133
	v_exp_f32_e32 v134, v134
	v_exp_f32_e32 v135, v135
	v_add_f32_e32 v118, 1.0, v118
	v_add_f32_e32 v119, 1.0, v119
	v_add_f32_e32 v120, 1.0, v120
	v_add_f32_e32 v121, 1.0, v121
	v_add_f32_e32 v122, 1.0, v122
	v_add_f32_e32 v123, 1.0, v123
	v_add_f32_e32 v124, 1.0, v124
	v_add_f32_e32 v125, 1.0, v125
	v_add_f32_e32 v126, 1.0, v126
	v_add_f32_e32 v127, 1.0, v127
	v_add_f32_e32 v128, 1.0, v128
	v_add_f32_e32 v129, 1.0, v129
	v_add_f32_e32 v130, 1.0, v130
	v_add_f32_e32 v131, 1.0, v131
	v_add_f32_e32 v132, 1.0, v132
	v_add_f32_e32 v133, 1.0, v133
	v_add_f32_e32 v134, 1.0, v134
	v_add_f32_e32 v135, 1.0, v135
	v_rcp_f32_e32 v118, v118
	v_rcp_f32_e32 v119, v119
	v_rcp_f32_e32 v120, v120
	v_rcp_f32_e32 v121, v121
	v_rcp_f32_e32 v122, v122
	v_rcp_f32_e32 v123, v123
	v_rcp_f32_e32 v124, v124
	v_rcp_f32_e32 v125, v125
	v_rcp_f32_e32 v126, v126
	v_rcp_f32_e32 v127, v127
	v_rcp_f32_e32 v128, v128
	v_rcp_f32_e32 v129, v129
	v_rcp_f32_e32 v130, v130
	v_rcp_f32_e32 v131, v131
	v_rcp_f32_e32 v132, v132
	v_rcp_f32_e32 v133, v133
	v_rcp_f32_e32 v134, v134
	v_rcp_f32_e32 v135, v135
	v_mul_f32_e32 v100, v100, v118
	v_mul_f32_e32 v101, v101, v119
	v_mul_f32_e32 v102, v102, v120
	v_mul_f32_e32 v103, v103, v121
	v_mul_f32_e32 v104, v104, v122
	v_mul_f32_e32 v105, v105, v123
	v_mul_f32_e32 v106, v106, v124
	v_mul_f32_e32 v107, v107, v125
	v_mul_f32_e32 v108, v108, v126
	v_mul_f32_e32 v109, v109, v127
	v_mul_f32_e32 v110, v110, v128
	v_mul_f32_e32 v111, v111, v129
	v_mul_f32_e32 v112, v112, v130
	v_mul_f32_e32 v113, v113, v131
	v_mul_f32_e32 v114, v114, v132
	v_mul_f32_e32 v115, v115, v133
	v_mul_f32_e32 v116, v116, v134
	v_mul_f32_e32 v117, v117, v135
	ds_write_b32 v81, v100
	ds_write_b32 v81, v101 offset:2048
	ds_write_b32 v81, v102 offset:4096
	ds_write_b32 v81, v103 offset:6144
	ds_write_b32 v81, v104 offset:8192
	ds_write_b32 v81, v105 offset:10240
	ds_write_b32 v81, v106 offset:12288
	ds_write_b32 v81, v107 offset:14336
	ds_write_b32 v81, v108 offset:16384
	ds_write_b32 v81, v109 offset:18432
	ds_write_b32 v81, v110 offset:20480
	ds_write_b32 v81, v111 offset:22528
	ds_write_b32 v81, v112 offset:24576
	ds_write_b32 v81, v113 offset:26624
	ds_write_b32 v81, v114 offset:28672
	ds_write_b32 v81, v115 offset:30720
	ds_write_b32 v81, v116 offset:32768
	ds_write_b32 v81, v117 offset:34816

.LBB0_787:
	s_mul_i32 s70, s10, 0x2400
	v_lshl_add_u64 v[12:13], s[70:71], 2, v[10:11]
	s_lshl_b32 s11, s10, 2
	s_add_i32 s11, s16, s11
	s_mov_b64 s[20:21], 0x9000
	v_mov_b32_e32 v0, s11
	global_load_dwordx2 v[100:101], v[12:13], off nt
	v_lshl_add_u64 v[12:13], v[12:13], 0, s[20:21]
	global_load_dwordx2 v[102:103], v[12:13], off nt
	v_lshl_add_u64 v[12:13], v[12:13], 0, s[20:21]
	global_load_dwordx2 v[104:105], v[12:13], off nt
	v_lshl_add_u64 v[12:13], v[12:13], 0, s[20:21]
	global_load_dwordx2 v[106:107], v[12:13], off nt
	v_lshl_add_u64 v[12:13], v[12:13], 0, s[20:21]
	global_load_dwordx2 v[108:109], v[12:13], off nt
	v_lshl_add_u64 v[12:13], v[12:13], 0, s[20:21]
	global_load_dwordx2 v[110:111], v[12:13], off nt
	v_lshl_add_u64 v[12:13], v[12:13], 0, s[20:21]
	global_load_dwordx2 v[112:113], v[12:13], off nt
	v_lshl_add_u64 v[12:13], v[12:13], 0, s[20:21]
	global_load_dwordx2 v[114:115], v[12:13], off nt
	v_lshl_add_u64 v[12:13], v[12:13], 0, s[20:21]
	global_load_dwordx2 v[116:117], v[12:13], off nt
	v_lshl_add_u64 v[12:13], v[12:13], 0, s[20:21]
	global_load_dwordx2 v[118:119], v[12:13], off nt
	v_lshl_add_u64 v[12:13], v[12:13], 0, s[20:21]
	global_load_dwordx2 v[120:121], v[12:13], off nt
	v_lshl_add_u64 v[12:13], v[12:13], 0, s[20:21]
	global_load_dwordx2 v[122:123], v[12:13], off nt
	v_lshl_add_u64 v[12:13], v[12:13], 0, s[20:21]
	global_load_dwordx2 v[124:125], v[12:13], off nt
	v_lshl_add_u64 v[12:13], v[12:13], 0, s[20:21]
	global_load_dwordx2 v[126:127], v[12:13], off nt
	v_lshl_add_u64 v[12:13], v[12:13], 0, s[20:21]
	global_load_dwordx2 v[128:129], v[12:13], off nt
	v_lshl_add_u64 v[12:13], v[12:13], 0, s[20:21]
	global_load_dwordx2 v[130:131], v[12:13], off nt
	v_lshl_add_u64 v[12:13], v[12:13], 0, s[20:21]
	global_load_dwordx2 v[132:133], v[12:13], off nt
	v_lshl_add_u64 v[12:13], v[12:13], 0, s[20:21]
	global_load_dwordx2 v[134:135], v[12:13], off nt
	v_lshl_add_u64 v[12:13], v[12:13], 0, s[20:21]
	global_load_dwordx2 v[136:137], v[12:13], off nt
	v_lshl_add_u64 v[12:13], v[12:13], 0, s[20:21]
	global_load_dwordx2 v[138:139], v[12:13], off nt
	v_lshl_add_u64 v[12:13], v[12:13], 0, s[20:21]
	global_load_dwordx2 v[140:141], v[12:13], off nt
	v_lshl_add_u64 v[12:13], v[12:13], 0, s[20:21]
	global_load_dwordx2 v[142:143], v[12:13], off nt
	v_lshl_add_u64 v[12:13], v[12:13], 0, s[20:21]
	global_load_dwordx2 v[144:145], v[12:13], off nt
	v_lshl_add_u64 v[12:13], v[12:13], 0, s[20:21]
	global_load_dwordx2 v[146:147], v[12:13], off nt
	v_lshl_add_u64 v[12:13], v[12:13], 0, s[20:21]
	global_load_dwordx2 v[148:149], v[12:13], off nt
	v_lshl_add_u64 v[12:13], v[12:13], 0, s[20:21]
	global_load_dwordx2 v[150:151], v[12:13], off nt
	v_lshl_add_u64 v[12:13], v[12:13], 0, s[20:21]
	global_load_dwordx2 v[152:153], v[12:13], off nt
	v_lshl_add_u64 v[12:13], v[12:13], 0, s[20:21]
	global_load_dwordx2 v[154:155], v[12:13], off nt
	v_lshl_add_u64 v[12:13], v[12:13], 0, s[20:21]
	global_load_dwordx2 v[156:157], v[12:13], off nt
	v_lshl_add_u64 v[12:13], v[12:13], 0, s[20:21]
	global_load_dwordx2 v[158:159], v[12:13], off nt
	v_lshl_add_u64 v[12:13], v[12:13], 0, s[20:21]
	global_load_dwordx2 v[160:161], v[12:13], off nt
	v_lshl_add_u64 v[12:13], v[12:13], 0, s[20:21]
	global_load_dwordx2 v[162:163], v[12:13], off nt
	ds_read_b128 v[164:167], v0 offset:0
	ds_read_b128 v[168:171], v0 offset:16
	ds_read_b128 v[172:175], v0 offset:4096
	ds_read_b128 v[176:179], v0 offset:4112
	ds_read_b128 v[190:193], v0 offset:8192
	ds_read_b128 v[194:197], v0 offset:8208
	ds_read_b128 v[198:201], v0 offset:12288
	ds_read_b128 v[202:205], v0 offset:12304
	ds_read_b128 v[206:209], v0 offset:16384
	ds_read_b128 v[210:213], v0 offset:16400
	ds_read_b128 v[214:217], v0 offset:20480
	ds_read_b128 v[218:221], v0 offset:20496
	ds_read_b128 v[222:225], v0 offset:24576
	ds_read_b128 v[226:229], v0 offset:24592
	ds_read_b128 v[240:243], v0 offset:28672
	ds_read_b128 v[244:247], v0 offset:28688
	ds_read_b128 v[248:251], v0 offset:32768
	ds_read_b128 v[68:71], v0 offset:32784
	s_waitcnt vmcnt(24) lgkmcnt(0)
	v_pk_fma_f32 v[20:21], v[100:101], v[164:165], v[20:21] op_sel_hi:[1,0,1]
	v_pk_fma_f32 v[48:49], v[100:101], v[172:173], v[48:49] op_sel_hi:[1,0,1]
	v_pk_fma_f32 v[46:47], v[100:101], v[190:191], v[46:47] op_sel_hi:[1,0,1]
	v_pk_fma_f32 v[42:43], v[100:101], v[198:199], v[42:43] op_sel_hi:[1,0,1]
	v_pk_fma_f32 v[38:39], v[100:101], v[206:207], v[38:39] op_sel_hi:[1,0,1]
	v_pk_fma_f32 v[30:31], v[100:101], v[214:215], v[30:31] op_sel_hi:[1,0,1]
	v_pk_fma_f32 v[28:29], v[100:101], v[222:223], v[28:29] op_sel_hi:[1,0,1]
	v_pk_fma_f32 v[24:25], v[100:101], v[240:241], v[24:25] op_sel_hi:[1,0,1]
	v_pk_fma_f32 v[22:23], v[100:101], v[248:249], v[22:23] op_sel_hi:[1,0,1]
	v_pk_fma_f32 v[20:21], v[102:103], v[164:165], v[20:21] op_sel:[0,1,0]
	v_pk_fma_f32 v[48:49], v[102:103], v[172:173], v[48:49] op_sel:[0,1,0]
	v_pk_fma_f32 v[46:47], v[102:103], v[190:191], v[46:47] op_sel:[0,1,0]
	v_pk_fma_f32 v[42:43], v[102:103], v[198:199], v[42:43] op_sel:[0,1,0]
	v_pk_fma_f32 v[38:39], v[102:103], v[206:207], v[38:39] op_sel:[0,1,0]
	v_pk_fma_f32 v[30:31], v[102:103], v[214:215], v[30:31] op_sel:[0,1,0]
	v_pk_fma_f32 v[28:29], v[102:103], v[222:223], v[28:29] op_sel:[0,1,0]
	v_pk_fma_f32 v[24:25], v[102:103], v[240:241], v[24:25] op_sel:[0,1,0]
	v_pk_fma_f32 v[22:23], v[102:103], v[248:249], v[22:23] op_sel:[0,1,0]
	v_pk_fma_f32 v[20:21], v[104:105], v[166:167], v[20:21] op_sel_hi:[1,0,1]
	v_pk_fma_f32 v[48:49], v[104:105], v[174:175], v[48:49] op_sel_hi:[1,0,1]
	v_pk_fma_f32 v[46:47], v[104:105], v[192:193], v[46:47] op_sel_hi:[1,0,1]
	v_pk_fma_f32 v[42:43], v[104:105], v[200:201], v[42:43] op_sel_hi:[1,0,1]
	v_pk_fma_f32 v[38:39], v[104:105], v[208:209], v[38:39] op_sel_hi:[1,0,1]
	v_pk_fma_f32 v[30:31], v[104:105], v[216:217], v[30:31] op_sel_hi:[1,0,1]
	v_pk_fma_f32 v[28:29], v[104:105], v[224:225], v[28:29] op_sel_hi:[1,0,1]
	v_pk_fma_f32 v[24:25], v[104:105], v[242:243], v[24:25] op_sel_hi:[1,0,1]
	v_pk_fma_f32 v[22:23], v[104:105], v[250:251], v[22:23] op_sel_hi:[1,0,1]
	v_pk_fma_f32 v[20:21], v[106:107], v[166:167], v[20:21] op_sel:[0,1,0]
	v_pk_fma_f32 v[48:49], v[106:107], v[174:175], v[48:49] op_sel:[0,1,0]
	v_pk_fma_f32 v[46:47], v[106:107], v[192:193], v[46:47] op_sel:[0,1,0]
	v_pk_fma_f32 v[42:43], v[106:107], v[200:201], v[42:43] op_sel:[0,1,0]
	v_pk_fma_f32 v[38:39], v[106:107], v[208:209], v[38:39] op_sel:[0,1,0]
	v_pk_fma_f32 v[30:31], v[106:107], v[216:217], v[30:31] op_sel:[0,1,0]
	v_pk_fma_f32 v[28:29], v[106:107], v[224:225], v[28:29] op_sel:[0,1,0]
	v_pk_fma_f32 v[24:25], v[106:107], v[242:243], v[24:25] op_sel:[0,1,0]
	v_pk_fma_f32 v[22:23], v[106:107], v[250:251], v[22:23] op_sel:[0,1,0]
	v_pk_fma_f32 v[20:21], v[108:109], v[168:169], v[20:21] op_sel_hi:[1,0,1]
	v_pk_fma_f32 v[48:49], v[108:109], v[176:177], v[48:49] op_sel_hi:[1,0,1]
	v_pk_fma_f32 v[46:47], v[108:109], v[194:195], v[46:47] op_sel_hi:[1,0,1]
	v_pk_fma_f32 v[42:43], v[108:109], v[202:203], v[42:43] op_sel_hi:[1,0,1]
	v_pk_fma_f32 v[38:39], v[108:109], v[210:211], v[38:39] op_sel_hi:[1,0,1]
	v_pk_fma_f32 v[30:31], v[108:109], v[218:219], v[30:31] op_sel_hi:[1,0,1]
	v_pk_fma_f32 v[28:29], v[108:109], v[226:227], v[28:29] op_sel_hi:[1,0,1]
	v_pk_fma_f32 v[24:25], v[108:109], v[244:245], v[24:25] op_sel_hi:[1,0,1]
	v_pk_fma_f32 v[22:23], v[108:109], v[68:69], v[22:23] op_sel_hi:[1,0,1]
	v_pk_fma_f32 v[20:21], v[110:111], v[168:169], v[20:21] op_sel:[0,1,0]
	v_pk_fma_f32 v[48:49], v[110:111], v[176:177], v[48:49] op_sel:[0,1,0]
	v_pk_fma_f32 v[46:47], v[110:111], v[194:195], v[46:47] op_sel:[0,1,0]
	v_pk_fma_f32 v[42:43], v[110:111], v[202:203], v[42:43] op_sel:[0,1,0]
	v_pk_fma_f32 v[38:39], v[110:111], v[210:211], v[38:39] op_sel:[0,1,0]
	v_pk_fma_f32 v[30:31], v[110:111], v[218:219], v[30:31] op_sel:[0,1,0]
	v_pk_fma_f32 v[28:29], v[110:111], v[226:227], v[28:29] op_sel:[0,1,0]
	v_pk_fma_f32 v[24:25], v[110:111], v[244:245], v[24:25] op_sel:[0,1,0]
	v_pk_fma_f32 v[22:23], v[110:111], v[68:69], v[22:23] op_sel:[0,1,0]
	v_pk_fma_f32 v[20:21], v[112:113], v[170:171], v[20:21] op_sel_hi:[1,0,1]
	v_pk_fma_f32 v[48:49], v[112:113], v[178:179], v[48:49] op_sel_hi:[1,0,1]
	v_pk_fma_f32 v[46:47], v[112:113], v[196:197], v[46:47] op_sel_hi:[1,0,1]
	v_pk_fma_f32 v[42:43], v[112:113], v[204:205], v[42:43] op_sel_hi:[1,0,1]
	v_pk_fma_f32 v[38:39], v[112:113], v[212:213], v[38:39] op_sel_hi:[1,0,1]
	v_pk_fma_f32 v[30:31], v[112:113], v[220:221], v[30:31] op_sel_hi:[1,0,1]
	v_pk_fma_f32 v[28:29], v[112:113], v[228:229], v[28:29] op_sel_hi:[1,0,1]
	v_pk_fma_f32 v[24:25], v[112:113], v[246:247], v[24:25] op_sel_hi:[1,0,1]
	v_pk_fma_f32 v[22:23], v[112:113], v[70:71], v[22:23] op_sel_hi:[1,0,1]
	v_pk_fma_f32 v[20:21], v[114:115], v[170:171], v[20:21] op_sel:[0,1,0]
	v_pk_fma_f32 v[48:49], v[114:115], v[178:179], v[48:49] op_sel:[0,1,0]
	v_pk_fma_f32 v[46:47], v[114:115], v[196:197], v[46:47] op_sel:[0,1,0]
	v_pk_fma_f32 v[42:43], v[114:115], v[204:205], v[42:43] op_sel:[0,1,0]
	v_pk_fma_f32 v[38:39], v[114:115], v[212:213], v[38:39] op_sel:[0,1,0]
	v_pk_fma_f32 v[30:31], v[114:115], v[220:221], v[30:31] op_sel:[0,1,0]
	v_pk_fma_f32 v[28:29], v[114:115], v[228:229], v[28:29] op_sel:[0,1,0]
	v_pk_fma_f32 v[24:25], v[114:115], v[246:247], v[24:25] op_sel:[0,1,0]
	v_pk_fma_f32 v[22:23], v[114:115], v[70:71], v[22:23] op_sel:[0,1,0]
	ds_read_b128 v[164:167], v0 offset:32
	ds_read_b128 v[168:171], v0 offset:48
	ds_read_b128 v[172:175], v0 offset:4128
	ds_read_b128 v[176:179], v0 offset:4144
	ds_read_b128 v[190:193], v0 offset:8224
	ds_read_b128 v[194:197], v0 offset:8240
	ds_read_b128 v[198:201], v0 offset:12320
	ds_read_b128 v[202:205], v0 offset:12336
	ds_read_b128 v[206:209], v0 offset:16416
	ds_read_b128 v[210:213], v0 offset:16432
	ds_read_b128 v[214:217], v0 offset:20512
	ds_read_b128 v[218:221], v0 offset:20528
	ds_read_b128 v[222:225], v0 offset:24608
	ds_read_b128 v[226:229], v0 offset:24624
	ds_read_b128 v[240:243], v0 offset:28704
	ds_read_b128 v[244:247], v0 offset:28720
	ds_read_b128 v[248:251], v0 offset:32800
	ds_read_b128 v[68:71], v0 offset:32816
	s_waitcnt vmcnt(16) lgkmcnt(0)
	v_pk_fma_f32 v[20:21], v[116:117], v[164:165], v[20:21] op_sel_hi:[1,0,1]
	v_pk_fma_f32 v[48:49], v[116:117], v[172:173], v[48:49] op_sel_hi:[1,0,1]
	v_pk_fma_f32 v[46:47], v[116:117], v[190:191], v[46:47] op_sel_hi:[1,0,1]
	v_pk_fma_f32 v[42:43], v[116:117], v[198:199], v[42:43] op_sel_hi:[1,0,1]
	v_pk_fma_f32 v[38:39], v[116:117], v[206:207], v[38:39] op_sel_hi:[1,0,1]
	v_pk_fma_f32 v[30:31], v[116:117], v[214:215], v[30:31] op_sel_hi:[1,0,1]
	v_pk_fma_f32 v[28:29], v[116:117], v[222:223], v[28:29] op_sel_hi:[1,0,1]
	v_pk_fma_f32 v[24:25], v[116:117], v[240:241], v[24:25] op_sel_hi:[1,0,1]
	v_pk_fma_f32 v[22:23], v[116:117], v[248:249], v[22:23] op_sel_hi:[1,0,1]
	v_pk_fma_f32 v[20:21], v[118:119], v[164:165], v[20:21] op_sel:[0,1,0]
	v_pk_fma_f32 v[48:49], v[118:119], v[172:173], v[48:49] op_sel:[0,1,0]
	v_pk_fma_f32 v[46:47], v[118:119], v[190:191], v[46:47] op_sel:[0,1,0]
	v_pk_fma_f32 v[42:43], v[118:119], v[198:199], v[42:43] op_sel:[0,1,0]
	v_pk_fma_f32 v[38:39], v[118:119], v[206:207], v[38:39] op_sel:[0,1,0]
	v_pk_fma_f32 v[30:31], v[118:119], v[214:215], v[30:31] op_sel:[0,1,0]
	v_pk_fma_f32 v[28:29], v[118:119], v[222:223], v[28:29] op_sel:[0,1,0]
	v_pk_fma_f32 v[24:25], v[118:119], v[240:241], v[24:25] op_sel:[0,1,0]
	v_pk_fma_f32 v[22:23], v[118:119], v[248:249], v[22:23] op_sel:[0,1,0]
	v_pk_fma_f32 v[20:21], v[120:121], v[166:167], v[20:21] op_sel_hi:[1,0,1]
	v_pk_fma_f32 v[48:49], v[120:121], v[174:175], v[48:49] op_sel_hi:[1,0,1]
	v_pk_fma_f32 v[46:47], v[120:121], v[192:193], v[46:47] op_sel_hi:[1,0,1]
	v_pk_fma_f32 v[42:43], v[120:121], v[200:201], v[42:43] op_sel_hi:[1,0,1]
	v_pk_fma_f32 v[38:39], v[120:121], v[208:209], v[38:39] op_sel_hi:[1,0,1]
	v_pk_fma_f32 v[30:31], v[120:121], v[216:217], v[30:31] op_sel_hi:[1,0,1]
	v_pk_fma_f32 v[28:29], v[120:121], v[224:225], v[28:29] op_sel_hi:[1,0,1]
	v_pk_fma_f32 v[24:25], v[120:121], v[242:243], v[24:25] op_sel_hi:[1,0,1]
	v_pk_fma_f32 v[22:23], v[120:121], v[250:251], v[22:23] op_sel_hi:[1,0,1]
	v_pk_fma_f32 v[20:21], v[122:123], v[166:167], v[20:21] op_sel:[0,1,0]
	v_pk_fma_f32 v[48:49], v[122:123], v[174:175], v[48:49] op_sel:[0,1,0]
	v_pk_fma_f32 v[46:47], v[122:123], v[192:193], v[46:47] op_sel:[0,1,0]
	v_pk_fma_f32 v[42:43], v[122:123], v[200:201], v[42:43] op_sel:[0,1,0]
	v_pk_fma_f32 v[38:39], v[122:123], v[208:209], v[38:39] op_sel:[0,1,0]
	v_pk_fma_f32 v[30:31], v[122:123], v[216:217], v[30:31] op_sel:[0,1,0]
	v_pk_fma_f32 v[28:29], v[122:123], v[224:225], v[28:29] op_sel:[0,1,0]
	v_pk_fma_f32 v[24:25], v[122:123], v[242:243], v[24:25] op_sel:[0,1,0]
	v_pk_fma_f32 v[22:23], v[122:123], v[250:251], v[22:23] op_sel:[0,1,0]
	v_pk_fma_f32 v[20:21], v[124:125], v[168:169], v[20:21] op_sel_hi:[1,0,1]
	v_pk_fma_f32 v[48:49], v[124:125], v[176:177], v[48:49] op_sel_hi:[1,0,1]
	v_pk_fma_f32 v[46:47], v[124:125], v[194:195], v[46:47] op_sel_hi:[1,0,1]
	v_pk_fma_f32 v[42:43], v[124:125], v[202:203], v[42:43] op_sel_hi:[1,0,1]
	v_pk_fma_f32 v[38:39], v[124:125], v[210:211], v[38:39] op_sel_hi:[1,0,1]
	v_pk_fma_f32 v[30:31], v[124:125], v[218:219], v[30:31] op_sel_hi:[1,0,1]
	v_pk_fma_f32 v[28:29], v[124:125], v[226:227], v[28:29] op_sel_hi:[1,0,1]
	v_pk_fma_f32 v[24:25], v[124:125], v[244:245], v[24:25] op_sel_hi:[1,0,1]
	v_pk_fma_f32 v[22:23], v[124:125], v[68:69], v[22:23] op_sel_hi:[1,0,1]
	v_pk_fma_f32 v[20:21], v[126:127], v[168:169], v[20:21] op_sel:[0,1,0]
	v_pk_fma_f32 v[48:49], v[126:127], v[176:177], v[48:49] op_sel:[0,1,0]
	v_pk_fma_f32 v[46:47], v[126:127], v[194:195], v[46:47] op_sel:[0,1,0]
	v_pk_fma_f32 v[42:43], v[126:127], v[202:203], v[42:43] op_sel:[0,1,0]
	v_pk_fma_f32 v[38:39], v[126:127], v[210:211], v[38:39] op_sel:[0,1,0]
	v_pk_fma_f32 v[30:31], v[126:127], v[218:219], v[30:31] op_sel:[0,1,0]
	v_pk_fma_f32 v[28:29], v[126:127], v[226:227], v[28:29] op_sel:[0,1,0]
	v_pk_fma_f32 v[24:25], v[126:127], v[244:245], v[24:25] op_sel:[0,1,0]
	v_pk_fma_f32 v[22:23], v[126:127], v[68:69], v[22:23] op_sel:[0,1,0]
	v_pk_fma_f32 v[20:21], v[128:129], v[170:171], v[20:21] op_sel_hi:[1,0,1]
	v_pk_fma_f32 v[48:49], v[128:129], v[178:179], v[48:49] op_sel_hi:[1,0,1]
	v_pk_fma_f32 v[46:47], v[128:129], v[196:197], v[46:47] op_sel_hi:[1,0,1]
	v_pk_fma_f32 v[42:43], v[128:129], v[204:205], v[42:43] op_sel_hi:[1,0,1]
	v_pk_fma_f32 v[38:39], v[128:129], v[212:213], v[38:39] op_sel_hi:[1,0,1]
	v_pk_fma_f32 v[30:31], v[128:129], v[220:221], v[30:31] op_sel_hi:[1,0,1]
	v_pk_fma_f32 v[28:29], v[128:129], v[228:229], v[28:29] op_sel_hi:[1,0,1]
	v_pk_fma_f32 v[24:25], v[128:129], v[246:247], v[24:25] op_sel_hi:[1,0,1]
	v_pk_fma_f32 v[22:23], v[128:129], v[70:71], v[22:23] op_sel_hi:[1,0,1]
	v_pk_fma_f32 v[20:21], v[130:131], v[170:171], v[20:21] op_sel:[0,1,0]
	v_pk_fma_f32 v[48:49], v[130:131], v[178:179], v[48:49] op_sel:[0,1,0]
	v_pk_fma_f32 v[46:47], v[130:131], v[196:197], v[46:47] op_sel:[0,1,0]
	v_pk_fma_f32 v[42:43], v[130:131], v[204:205], v[42:43] op_sel:[0,1,0]
	v_pk_fma_f32 v[38:39], v[130:131], v[212:213], v[38:39] op_sel:[0,1,0]
	v_pk_fma_f32 v[30:31], v[130:131], v[220:221], v[30:31] op_sel:[0,1,0]
	v_pk_fma_f32 v[28:29], v[130:131], v[228:229], v[28:29] op_sel:[0,1,0]
	v_pk_fma_f32 v[24:25], v[130:131], v[246:247], v[24:25] op_sel:[0,1,0]
	v_pk_fma_f32 v[22:23], v[130:131], v[70:71], v[22:23] op_sel:[0,1,0]
	ds_read_b128 v[164:167], v0 offset:64
	ds_read_b128 v[168:171], v0 offset:80
	ds_read_b128 v[172:175], v0 offset:4160
	ds_read_b128 v[176:179], v0 offset:4176
	ds_read_b128 v[190:193], v0 offset:8256
	ds_read_b128 v[194:197], v0 offset:8272
	ds_read_b128 v[198:201], v0 offset:12352
	ds_read_b128 v[202:205], v0 offset:12368
	ds_read_b128 v[206:209], v0 offset:16448
	ds_read_b128 v[210:213], v0 offset:16464
	ds_read_b128 v[214:217], v0 offset:20544
	ds_read_b128 v[218:221], v0 offset:20560
	ds_read_b128 v[222:225], v0 offset:24640
	ds_read_b128 v[226:229], v0 offset:24656
	ds_read_b128 v[240:243], v0 offset:28736
	ds_read_b128 v[244:247], v0 offset:28752
	ds_read_b128 v[248:251], v0 offset:32832
	ds_read_b128 v[68:71], v0 offset:32848
	s_waitcnt vmcnt(8) lgkmcnt(0)
	v_pk_fma_f32 v[20:21], v[132:133], v[164:165], v[20:21] op_sel_hi:[1,0,1]
	v_pk_fma_f32 v[48:49], v[132:133], v[172:173], v[48:49] op_sel_hi:[1,0,1]
	v_pk_fma_f32 v[46:47], v[132:133], v[190:191], v[46:47] op_sel_hi:[1,0,1]
	v_pk_fma_f32 v[42:43], v[132:133], v[198:199], v[42:43] op_sel_hi:[1,0,1]
	v_pk_fma_f32 v[38:39], v[132:133], v[206:207], v[38:39] op_sel_hi:[1,0,1]
	v_pk_fma_f32 v[30:31], v[132:133], v[214:215], v[30:31] op_sel_hi:[1,0,1]
	v_pk_fma_f32 v[28:29], v[132:133], v[222:223], v[28:29] op_sel_hi:[1,0,1]
	v_pk_fma_f32 v[24:25], v[132:133], v[240:241], v[24:25] op_sel_hi:[1,0,1]
	v_pk_fma_f32 v[22:23], v[132:133], v[248:249], v[22:23] op_sel_hi:[1,0,1]
	v_pk_fma_f32 v[20:21], v[134:135], v[164:165], v[20:21] op_sel:[0,1,0]
	v_pk_fma_f32 v[48:49], v[134:135], v[172:173], v[48:49] op_sel:[0,1,0]
	v_pk_fma_f32 v[46:47], v[134:135], v[190:191], v[46:47] op_sel:[0,1,0]
	v_pk_fma_f32 v[42:43], v[134:135], v[198:199], v[42:43] op_sel:[0,1,0]
	v_pk_fma_f32 v[38:39], v[134:135], v[206:207], v[38:39] op_sel:[0,1,0]
	v_pk_fma_f32 v[30:31], v[134:135], v[214:215], v[30:31] op_sel:[0,1,0]
	v_pk_fma_f32 v[28:29], v[134:135], v[222:223], v[28:29] op_sel:[0,1,0]
	v_pk_fma_f32 v[24:25], v[134:135], v[240:241], v[24:25] op_sel:[0,1,0]
	v_pk_fma_f32 v[22:23], v[134:135], v[248:249], v[22:23] op_sel:[0,1,0]
	v_pk_fma_f32 v[20:21], v[136:137], v[166:167], v[20:21] op_sel_hi:[1,0,1]
	v_pk_fma_f32 v[48:49], v[136:137], v[174:175], v[48:49] op_sel_hi:[1,0,1]
	v_pk_fma_f32 v[46:47], v[136:137], v[192:193], v[46:47] op_sel_hi:[1,0,1]
	v_pk_fma_f32 v[42:43], v[136:137], v[200:201], v[42:43] op_sel_hi:[1,0,1]
	v_pk_fma_f32 v[38:39], v[136:137], v[208:209], v[38:39] op_sel_hi:[1,0,1]
	v_pk_fma_f32 v[30:31], v[136:137], v[216:217], v[30:31] op_sel_hi:[1,0,1]
	v_pk_fma_f32 v[28:29], v[136:137], v[224:225], v[28:29] op_sel_hi:[1,0,1]
	v_pk_fma_f32 v[24:25], v[136:137], v[242:243], v[24:25] op_sel_hi:[1,0,1]
	v_pk_fma_f32 v[22:23], v[136:137], v[250:251], v[22:23] op_sel_hi:[1,0,1]
	v_pk_fma_f32 v[20:21], v[138:139], v[166:167], v[20:21] op_sel:[0,1,0]
	v_pk_fma_f32 v[48:49], v[138:139], v[174:175], v[48:49] op_sel:[0,1,0]
	v_pk_fma_f32 v[46:47], v[138:139], v[192:193], v[46:47] op_sel:[0,1,0]
	v_pk_fma_f32 v[42:43], v[138:139], v[200:201], v[42:43] op_sel:[0,1,0]
	v_pk_fma_f32 v[38:39], v[138:139], v[208:209], v[38:39] op_sel:[0,1,0]
	v_pk_fma_f32 v[30:31], v[138:139], v[216:217], v[30:31] op_sel:[0,1,0]
	v_pk_fma_f32 v[28:29], v[138:139], v[224:225], v[28:29] op_sel:[0,1,0]
	v_pk_fma_f32 v[24:25], v[138:139], v[242:243], v[24:25] op_sel:[0,1,0]
	v_pk_fma_f32 v[22:23], v[138:139], v[250:251], v[22:23] op_sel:[0,1,0]
	v_pk_fma_f32 v[20:21], v[140:141], v[168:169], v[20:21] op_sel_hi:[1,0,1]
	v_pk_fma_f32 v[48:49], v[140:141], v[176:177], v[48:49] op_sel_hi:[1,0,1]
	v_pk_fma_f32 v[46:47], v[140:141], v[194:195], v[46:47] op_sel_hi:[1,0,1]
	v_pk_fma_f32 v[42:43], v[140:141], v[202:203], v[42:43] op_sel_hi:[1,0,1]
	v_pk_fma_f32 v[38:39], v[140:141], v[210:211], v[38:39] op_sel_hi:[1,0,1]
	v_pk_fma_f32 v[30:31], v[140:141], v[218:219], v[30:31] op_sel_hi:[1,0,1]
	v_pk_fma_f32 v[28:29], v[140:141], v[226:227], v[28:29] op_sel_hi:[1,0,1]
	v_pk_fma_f32 v[24:25], v[140:141], v[244:245], v[24:25] op_sel_hi:[1,0,1]
	v_pk_fma_f32 v[22:23], v[140:141], v[68:69], v[22:23] op_sel_hi:[1,0,1]
	v_pk_fma_f32 v[20:21], v[142:143], v[168:169], v[20:21] op_sel:[0,1,0]
	v_pk_fma_f32 v[48:49], v[142:143], v[176:177], v[48:49] op_sel:[0,1,0]
	v_pk_fma_f32 v[46:47], v[142:143], v[194:195], v[46:47] op_sel:[0,1,0]
	v_pk_fma_f32 v[42:43], v[142:143], v[202:203], v[42:43] op_sel:[0,1,0]
	v_pk_fma_f32 v[38:39], v[142:143], v[210:211], v[38:39] op_sel:[0,1,0]
	v_pk_fma_f32 v[30:31], v[142:143], v[218:219], v[30:31] op_sel:[0,1,0]
	v_pk_fma_f32 v[28:29], v[142:143], v[226:227], v[28:29] op_sel:[0,1,0]
	v_pk_fma_f32 v[24:25], v[142:143], v[244:245], v[24:25] op_sel:[0,1,0]
	v_pk_fma_f32 v[22:23], v[142:143], v[68:69], v[22:23] op_sel:[0,1,0]
	v_pk_fma_f32 v[20:21], v[144:145], v[170:171], v[20:21] op_sel_hi:[1,0,1]
	v_pk_fma_f32 v[48:49], v[144:145], v[178:179], v[48:49] op_sel_hi:[1,0,1]
	v_pk_fma_f32 v[46:47], v[144:145], v[196:197], v[46:47] op_sel_hi:[1,0,1]
	v_pk_fma_f32 v[42:43], v[144:145], v[204:205], v[42:43] op_sel_hi:[1,0,1]
	v_pk_fma_f32 v[38:39], v[144:145], v[212:213], v[38:39] op_sel_hi:[1,0,1]
	v_pk_fma_f32 v[30:31], v[144:145], v[220:221], v[30:31] op_sel_hi:[1,0,1]
	v_pk_fma_f32 v[28:29], v[144:145], v[228:229], v[28:29] op_sel_hi:[1,0,1]
	v_pk_fma_f32 v[24:25], v[144:145], v[246:247], v[24:25] op_sel_hi:[1,0,1]
	v_pk_fma_f32 v[22:23], v[144:145], v[70:71], v[22:23] op_sel_hi:[1,0,1]
	v_pk_fma_f32 v[20:21], v[146:147], v[170:171], v[20:21] op_sel:[0,1,0]
	v_pk_fma_f32 v[48:49], v[146:147], v[178:179], v[48:49] op_sel:[0,1,0]
	v_pk_fma_f32 v[46:47], v[146:147], v[196:197], v[46:47] op_sel:[0,1,0]
	v_pk_fma_f32 v[42:43], v[146:147], v[204:205], v[42:43] op_sel:[0,1,0]
	v_pk_fma_f32 v[38:39], v[146:147], v[212:213], v[38:39] op_sel:[0,1,0]
	v_pk_fma_f32 v[30:31], v[146:147], v[220:221], v[30:31] op_sel:[0,1,0]
	v_pk_fma_f32 v[28:29], v[146:147], v[228:229], v[28:29] op_sel:[0,1,0]
	v_pk_fma_f32 v[24:25], v[146:147], v[246:247], v[24:25] op_sel:[0,1,0]
	v_pk_fma_f32 v[22:23], v[146:147], v[70:71], v[22:23] op_sel:[0,1,0]
	ds_read_b128 v[164:167], v0 offset:96
	ds_read_b128 v[168:171], v0 offset:112
	ds_read_b128 v[172:175], v0 offset:4192
	ds_read_b128 v[176:179], v0 offset:4208
	ds_read_b128 v[190:193], v0 offset:8288
	ds_read_b128 v[194:197], v0 offset:8304
	ds_read_b128 v[198:201], v0 offset:12384
	ds_read_b128 v[202:205], v0 offset:12400
	ds_read_b128 v[206:209], v0 offset:16480
	ds_read_b128 v[210:213], v0 offset:16496
	ds_read_b128 v[214:217], v0 offset:20576
	ds_read_b128 v[218:221], v0 offset:20592
	ds_read_b128 v[222:225], v0 offset:24672
	ds_read_b128 v[226:229], v0 offset:24688
	ds_read_b128 v[240:243], v0 offset:28768
	ds_read_b128 v[244:247], v0 offset:28784
	ds_read_b128 v[248:251], v0 offset:32864
	ds_read_b128 v[68:71], v0 offset:32880
	s_waitcnt vmcnt(0) lgkmcnt(0)
	v_pk_fma_f32 v[20:21], v[148:149], v[164:165], v[20:21] op_sel_hi:[1,0,1]
	v_pk_fma_f32 v[48:49], v[148:149], v[172:173], v[48:49] op_sel_hi:[1,0,1]
	v_pk_fma_f32 v[46:47], v[148:149], v[190:191], v[46:47] op_sel_hi:[1,0,1]
	v_pk_fma_f32 v[42:43], v[148:149], v[198:199], v[42:43] op_sel_hi:[1,0,1]
	v_pk_fma_f32 v[38:39], v[148:149], v[206:207], v[38:39] op_sel_hi:[1,0,1]
	v_pk_fma_f32 v[30:31], v[148:149], v[214:215], v[30:31] op_sel_hi:[1,0,1]
	v_pk_fma_f32 v[28:29], v[148:149], v[222:223], v[28:29] op_sel_hi:[1,0,1]
	v_pk_fma_f32 v[24:25], v[148:149], v[240:241], v[24:25] op_sel_hi:[1,0,1]
	v_pk_fma_f32 v[22:23], v[148:149], v[248:249], v[22:23] op_sel_hi:[1,0,1]
	v_pk_fma_f32 v[20:21], v[150:151], v[164:165], v[20:21] op_sel:[0,1,0]
	v_pk_fma_f32 v[48:49], v[150:151], v[172:173], v[48:49] op_sel:[0,1,0]
	v_pk_fma_f32 v[46:47], v[150:151], v[190:191], v[46:47] op_sel:[0,1,0]
	v_pk_fma_f32 v[42:43], v[150:151], v[198:199], v[42:43] op_sel:[0,1,0]
	v_pk_fma_f32 v[38:39], v[150:151], v[206:207], v[38:39] op_sel:[0,1,0]
	v_pk_fma_f32 v[30:31], v[150:151], v[214:215], v[30:31] op_sel:[0,1,0]
	v_pk_fma_f32 v[28:29], v[150:151], v[222:223], v[28:29] op_sel:[0,1,0]
	v_pk_fma_f32 v[24:25], v[150:151], v[240:241], v[24:25] op_sel:[0,1,0]
	v_pk_fma_f32 v[22:23], v[150:151], v[248:249], v[22:23] op_sel:[0,1,0]
	v_pk_fma_f32 v[20:21], v[152:153], v[166:167], v[20:21] op_sel_hi:[1,0,1]
	v_pk_fma_f32 v[48:49], v[152:153], v[174:175], v[48:49] op_sel_hi:[1,0,1]
	v_pk_fma_f32 v[46:47], v[152:153], v[192:193], v[46:47] op_sel_hi:[1,0,1]
	v_pk_fma_f32 v[42:43], v[152:153], v[200:201], v[42:43] op_sel_hi:[1,0,1]
	v_pk_fma_f32 v[38:39], v[152:153], v[208:209], v[38:39] op_sel_hi:[1,0,1]
	v_pk_fma_f32 v[30:31], v[152:153], v[216:217], v[30:31] op_sel_hi:[1,0,1]
	v_pk_fma_f32 v[28:29], v[152:153], v[224:225], v[28:29] op_sel_hi:[1,0,1]
	v_pk_fma_f32 v[24:25], v[152:153], v[242:243], v[24:25] op_sel_hi:[1,0,1]
	v_pk_fma_f32 v[22:23], v[152:153], v[250:251], v[22:23] op_sel_hi:[1,0,1]
	v_pk_fma_f32 v[20:21], v[154:155], v[166:167], v[20:21] op_sel:[0,1,0]
	v_pk_fma_f32 v[48:49], v[154:155], v[174:175], v[48:49] op_sel:[0,1,0]
	v_pk_fma_f32 v[46:47], v[154:155], v[192:193], v[46:47] op_sel:[0,1,0]
	v_pk_fma_f32 v[42:43], v[154:155], v[200:201], v[42:43] op_sel:[0,1,0]
	v_pk_fma_f32 v[38:39], v[154:155], v[208:209], v[38:39] op_sel:[0,1,0]
	v_pk_fma_f32 v[30:31], v[154:155], v[216:217], v[30:31] op_sel:[0,1,0]
	v_pk_fma_f32 v[28:29], v[154:155], v[224:225], v[28:29] op_sel:[0,1,0]
	v_pk_fma_f32 v[24:25], v[154:155], v[242:243], v[24:25] op_sel:[0,1,0]
	v_pk_fma_f32 v[22:23], v[154:155], v[250:251], v[22:23] op_sel:[0,1,0]
	v_pk_fma_f32 v[20:21], v[156:157], v[168:169], v[20:21] op_sel_hi:[1,0,1]
	v_pk_fma_f32 v[48:49], v[156:157], v[176:177], v[48:49] op_sel_hi:[1,0,1]
	v_pk_fma_f32 v[46:47], v[156:157], v[194:195], v[46:47] op_sel_hi:[1,0,1]
	v_pk_fma_f32 v[42:43], v[156:157], v[202:203], v[42:43] op_sel_hi:[1,0,1]
	v_pk_fma_f32 v[38:39], v[156:157], v[210:211], v[38:39] op_sel_hi:[1,0,1]
	v_pk_fma_f32 v[30:31], v[156:157], v[218:219], v[30:31] op_sel_hi:[1,0,1]
	v_pk_fma_f32 v[28:29], v[156:157], v[226:227], v[28:29] op_sel_hi:[1,0,1]
	v_pk_fma_f32 v[24:25], v[156:157], v[244:245], v[24:25] op_sel_hi:[1,0,1]
	v_pk_fma_f32 v[22:23], v[156:157], v[68:69], v[22:23] op_sel_hi:[1,0,1]
	v_pk_fma_f32 v[20:21], v[158:159], v[168:169], v[20:21] op_sel:[0,1,0]
	v_pk_fma_f32 v[48:49], v[158:159], v[176:177], v[48:49] op_sel:[0,1,0]
	v_pk_fma_f32 v[46:47], v[158:159], v[194:195], v[46:47] op_sel:[0,1,0]
	v_pk_fma_f32 v[42:43], v[158:159], v[202:203], v[42:43] op_sel:[0,1,0]
	v_pk_fma_f32 v[38:39], v[158:159], v[210:211], v[38:39] op_sel:[0,1,0]
	v_pk_fma_f32 v[30:31], v[158:159], v[218:219], v[30:31] op_sel:[0,1,0]
	v_pk_fma_f32 v[28:29], v[158:159], v[226:227], v[28:29] op_sel:[0,1,0]
	v_pk_fma_f32 v[24:25], v[158:159], v[244:245], v[24:25] op_sel:[0,1,0]
	v_pk_fma_f32 v[22:23], v[158:159], v[68:69], v[22:23] op_sel:[0,1,0]
	v_pk_fma_f32 v[20:21], v[160:161], v[170:171], v[20:21] op_sel_hi:[1,0,1]
	v_pk_fma_f32 v[48:49], v[160:161], v[178:179], v[48:49] op_sel_hi:[1,0,1]
	v_pk_fma_f32 v[46:47], v[160:161], v[196:197], v[46:47] op_sel_hi:[1,0,1]
	v_pk_fma_f32 v[42:43], v[160:161], v[204:205], v[42:43] op_sel_hi:[1,0,1]
	v_pk_fma_f32 v[38:39], v[160:161], v[212:213], v[38:39] op_sel_hi:[1,0,1]
	v_pk_fma_f32 v[30:31], v[160:161], v[220:221], v[30:31] op_sel_hi:[1,0,1]
	v_pk_fma_f32 v[28:29], v[160:161], v[228:229], v[28:29] op_sel_hi:[1,0,1]
	v_pk_fma_f32 v[24:25], v[160:161], v[246:247], v[24:25] op_sel_hi:[1,0,1]
	v_pk_fma_f32 v[22:23], v[160:161], v[70:71], v[22:23] op_sel_hi:[1,0,1]
	v_pk_fma_f32 v[20:21], v[162:163], v[170:171], v[20:21] op_sel:[0,1,0]
	v_pk_fma_f32 v[48:49], v[162:163], v[178:179], v[48:49] op_sel:[0,1,0]
	v_pk_fma_f32 v[46:47], v[162:163], v[196:197], v[46:47] op_sel:[0,1,0]
	v_pk_fma_f32 v[42:43], v[162:163], v[204:205], v[42:43] op_sel:[0,1,0]
	v_pk_fma_f32 v[38:39], v[162:163], v[212:213], v[38:39] op_sel:[0,1,0]
	v_pk_fma_f32 v[30:31], v[162:163], v[220:221], v[30:31] op_sel:[0,1,0]
	v_pk_fma_f32 v[28:29], v[162:163], v[228:229], v[28:29] op_sel:[0,1,0]
	v_pk_fma_f32 v[24:25], v[162:163], v[246:247], v[24:25] op_sel:[0,1,0]
	v_pk_fma_f32 v[22:23], v[162:163], v[70:71], v[22:23] op_sel:[0,1,0]
	s_add_i32 s10, s10, 32
	s_cmpk_lt_u32 s10, 0x80
	s_cbranch_scc1 .LBB0_787
	v_add_u32_e32 v0, 0x9000, v82
	ds_write2_b32 v0, v20, v21 offset1:1
	v_add_u32_e32 v0, 0x9200, v82
	ds_write2_b32 v0, v48, v49 offset1:1
	v_add_u32_e32 v0, 0x9400, v82
	ds_write2_b32 v0, v46, v47 offset1:1
	v_add_u32_e32 v0, 0x9600, v82
	ds_write2_b32 v0, v42, v43 offset1:1
	v_add_u32_e32 v0, 0x9800, v82
	ds_write2_b32 v0, v38, v39 offset1:1
	v_add_u32_e32 v0, 0x9a00, v82
	ds_write2_b32 v0, v30, v31 offset1:1
	v_add_u32_e32 v0, 0x9c00, v82
	ds_write2_b32 v0, v28, v29 offset1:1
	v_add_u32_e32 v0, 0x9e00, v82
	ds_write2_b32 v0, v24, v25 offset1:1
	v_add_u32_e32 v0, 0xa000, v82
	ds_write2_b32 v0, v22, v23 offset1:1
	s_waitcnt lgkmcnt(0)
	s_barrier
	s_and_saveexec_b64 s[10:11], s[6:7]
	v_readlane_b32 s66, v253, 9
	v_readlane_b32 s68, v253, 11
	v_readlane_b32 s72, v253, 13
	v_readlane_b32 s52, v253, 6
	v_readlane_b32 s53, v253, 7
	v_readlane_b32 s54, v253, 8
	s_mov_b32 s55, 0xffff
	s_mov_b32 s60, 0x16000
	s_mov_b32 s61, 0x31000
	s_mov_b32 s62, 0x79000
	s_mov_b32 s64, 0x478bbced
	v_readlane_b32 s67, v253, 10
	v_readlane_b32 s69, v253, 12
	v_readlane_b32 s73, v253, 14
	s_cbranch_execz .LBB0_778
	s_mul_i32 s13, s8, 0x2400
	s_ashr_i32 s12, s12, 3
	s_add_i32 s20, s13, s0
	s_mul_hi_i32 s13, s12, 0x55555556
	s_lshr_b32 s21, s13, 31
	s_add_i32 s21, s13, s21
	s_mul_i32 s13, s21, 3
	s_sub_i32 s12, s12, s13
	s_cmp_eq_u32 s12, 0
	s_mul_i32 s21, s21, 9
	s_mul_i32 s18, s8, 9
	s_cselect_b64 s[12:13], -1, 0
	s_lshl_b64 s[8:9], s[8:9], 8
	s_ashr_i32 s22, s21, 31
	s_add_u32 s8, s8, s21
	s_addc_u32 s9, s9, s22
	s_and_b32 s21, s0, 0x380
	v_or_b32_e32 v10, s20, v3
	v_ashrrev_i32_e32 v11, 31, v10
	s_lshl_b32 s70, s21, 1
	v_lshl_add_u64 v[10:11], v[10:11], 2, s[50:51]
	v_lshl_add_u64 v[12:13], s[0:1], 2, v[4:5]
	v_lshl_add_u64 v[14:15], v[6:7], 0, s[70:71]
	s_mov_b64 s[0:1], 0
	v_mov_b32_e32 v0, v239
	s_branch .LBB0_791
